# wait_mod acquire: drop the L2 write-back (buffer_wbl2) from the acquire after the mod-arrival poll, keep the invalidate (this workgroup's earlier writes are released by grid barrier 1)
# speedup vs baseline: 1.0021x; 1.0021x over previous
; DI int tid_() { int t = threadIdx.x; asm volatile("" : "+v"(t)); return t; }
; DI void wait_mod(const Params& p) {
;   if (threadIdx.x == 0) {
;     while (__hip_atomic_load(p.modctr, __ATOMIC_RELAXED, __HIP_MEMORY_SCOPE_AGENT) < 384u) __builtin_amdgcn_s_sleep(8);
;     __threadfence();
;   }
;   __syncthreads();
; }
; DI void phase1(const Params& p) {
;   const int t_ = tid_(); const int lane = t_ & 63, w = t_ >> 6;
;   const int gw = blockIdx.x * NWV + w, nw = gridDim.x * NWV;
;   for (int R0 = gw; R0 < NT + NC; R0 += 2 * nw) {
;     const int R1 = R0 + nw; const bool has1 = R1 < NT + NC;
;     const float* src0 = (R0 < NT) ? p.x + (size_t)R0 * DM : p.ctx + (size_t)(R0 - NT) * DM;
;     const float* src1 = has1 ? ((R1 < NT) ? p.x + (size_t)R1 * DM : p.ctx + (size_t)(R1 - NT) * DM) : src0;
;     const float* md0 = p.mod + ((R0 < NT) ? (R0 >> 11) : 32) * 6144;
;     const float* md1 = p.mod + ((has1 && R1 < NT) ? (R1 >> 11) : 32) * 6144;
;     float4 v0[4], v1[4]; float s0 = 0.f, s1 = 0.f;
; #pragma unroll
;     for (int i = 0; i < 4; ++i) { v0[i] = *(const float4*)(src0 + lane * 4 + 256 * i); v1[i] = *(const float4*)(src1 + lane * 4 + 256 * i); }
.LBB0_98:
	s_sleep 8
	global_load_dword v2, v1, s[6:7] sc1
	s_waitcnt vmcnt(0)
	v_cmp_gt_u32_e32 vcc, s8, v2
	s_cbranch_vccnz .LBB0_98
.LBB0_99:
	buffer_inv sc1
.LBB0_100:
	s_or_b64 exec, exec, s[4:5]
	v_mov_b32_e32 v2, v220
	s_barrier
	s_lshl_b32 s4, s2, 3
	v_ashrrev_i32_e32 v1, 6, v2
	v_add_u32_e32 v34, s4, v1
	s_mov_b32 s27, 0x12000
	s_lshl_b32 s33, s3, 3
	v_cmp_gt_i32_e32 vcc, s27, v34
	v_mbcnt_lo_u32_b32 v221, -1, 0
	v_writelane_b32 v252, s4, 2
	s_and_saveexec_b64 s[12:13], vcc
	s_cbranch_execz .LBB0_117
	v_lshlrev_b32_e32 v1, 2, v2
	v_mbcnt_hi_u32_b32 v3, -1, v221
	v_and_b32_e32 v4, 0xfc, v1
	v_and_b32_e32 v1, 64, v3
	v_add_u32_e32 v5, 64, v1
	v_xor_b32_e32 v1, 32, v3
	v_cmp_lt_i32_e32 vcc, v1, v5
	v_xor_b32_e32 v6, 16, v3
	s_load_dwordx4 s[8:11], s[0:1], 0xb8
	v_cndmask_b32_e32 v1, v3, v1, vcc
	v_cmp_lt_i32_e32 vcc, v6, v5
	s_load_dwordx2 s[16:17], s[0:1], 0x0
	s_load_dwordx2 s[18:19], s[0:1], 0x10
	s_load_dwordx2 s[4:5], s[0:1], 0x30
	v_cndmask_b32_e32 v6, v3, v6, vcc
	v_lshlrev_b32_e32 v39, 2, v6
	v_xor_b32_e32 v6, 8, v3
	v_cmp_lt_i32_e32 vcc, v6, v5
	v_and_b32_e32 v2, 63, v2
	v_lshlrev_b32_e32 v46, 3, v2
	v_cndmask_b32_e32 v6, v3, v6, vcc
	v_lshlrev_b32_e32 v41, 2, v6
	v_xor_b32_e32 v6, 4, v3
	v_cmp_lt_i32_e32 vcc, v6, v5
	v_add_u32_e32 v2, s33, v34
	s_lshl_b32 s14, s3, 4
	v_cndmask_b32_e32 v6, v3, v6, vcc
	v_lshlrev_b32_e32 v43, 2, v6
	v_xor_b32_e32 v6, 2, v3
	v_cmp_lt_i32_e32 vcc, v6, v5
	v_ashrrev_i32_e32 v35, 31, v34
	v_mov_b32_e32 v37, 0
	v_cndmask_b32_e32 v6, v3, v6, vcc
	v_lshlrev_b32_e32 v59, 2, v6
	v_xor_b32_e32 v6, 1, v3
	v_cmp_lt_i32_e32 vcc, v6, v5
	v_lshlrev_b32_e32 v36, 2, v4
	s_ashr_i32 s15, s14, 31
	v_cndmask_b32_e32 v3, v3, v6, vcc
	v_lshlrev_b32_e32 v67, 2, v3
	v_ashrrev_i32_e32 v3, 31, v2
	v_lshlrev_b64 v[6:7], 11, v[2:3]
	s_waitcnt vmcnt(0) lgkmcnt(0)
	v_lshl_add_u64 v[48:49], s[10:11], 0, v[6:7]
	v_lshlrev_b64 v[6:7], 11, v[34:35]
	v_lshlrev_b32_e32 v54, 2, v4
	v_lshlrev_b32_e32 v1, 2, v1
	v_or_b32_e32 v38, 0x100, v4
	v_or_b32_e32 v40, 0x200, v4
	v_or_b32_e32 v42, 0x300, v4
	v_lshl_add_u64 v[44:45], s[4:5], 0, v[36:37]
	v_mov_b32_e32 v47, v37
	s_lshl_b64 s[20:21], s[14:15], 11
	v_lshl_add_u64 v[50:51], s[10:11], 0, v[6:7]
	v_lshlrev_b64 v[52:53], 12, v[2:3]
	s_lshl_b64 s[10:11], s[14:15], 12
	s_mov_b64 s[22:23], 0
	s_mov_b32 s30, 0x10000
	v_mov_b32_e32 v76, s19
	v_mov_b32_e32 v77, s17
	v_mov_b32_e32 v78, s18
	v_mov_b32_e32 v79, s16
	s_mov_b32 s31, 0xffff
	v_mov_b32_e32 v56, v54
	v_mov_b32_e32 v57, v37
	s_mov_b64 s[24:25], 0x1000
	s_mov_b32 s26, 0x3a800000
	v_mov_b32_e32 v58, 0x358637bd
	s_mov_b32 s34, 0x800000
	s_mov_b32 s35, 0x11fff
	s_mov_b64 s[28:29], 0
	v_mov_b32_e32 v80, v34
	s_branch .LBB0_103
